# flag grid barrier generalised to any grid size up to 256 (master ignores flags of absent workgroups); otherwise same as v60
# speedup vs baseline: 1.0037x; 1.0037x over previous
; __global__ void __launch_bounds__(NTHR, 2) mk_fwd(Args a_by_value) {
;     ...
;         if (ph + 1 < ph_hi) cg::this_grid().sync();
.Lfb_fast:
	buffer_wbl2 sc1
	s_load_dwordx2 s[6:7], s[0:1], 0xb0
	s_load_dword s8, s[0:1], 0xc0
	s_add_u32 s100, s100, 1
	v_mov_b32_e32 v2, 1
	s_lshl_b32 s9, s2, 2
	s_add_u32 s9, s9, 0x4000
	v_mov_b32_e32 v0, s9
	s_waitcnt vmcnt(0) lgkmcnt(0)
	global_atomic_add v0, v2, s[6:7]
	s_cmp_lg_u32 s2, 0
	s_cbranch_scc1 .Lfb_member
	s_mov_b64 s[10:11], exec
	s_mov_b64 exec, -1
	v_lshlrev_b32_e32 v0, 4, v187
	v_add_u32_e32 v0, 0x4000, v0
	v_lshlrev_b32_e32 v3, 2, v187
	v_mov_b32_e32 v8, s100
	s_mov_b32 s13, 0x4000
.Lfb_spin_all:
	global_load_dwordx4 v[4:7], v0, s[6:7] sc1
	s_waitcnt vmcnt(0)
	v_cmp_gt_u32_e32 vcc, s8, v3
	v_add_u32_e32 v9, 1, v3
	s_nop 0
	v_cndmask_b32_e32 v4, v8, v4, vcc
	v_cmp_gt_u32_e32 vcc, s8, v9
	v_add_u32_e32 v9, 2, v3
	s_nop 0
	v_cndmask_b32_e32 v5, v8, v5, vcc
	v_cmp_gt_u32_e32 vcc, s8, v9
	v_add_u32_e32 v9, 3, v3
	s_nop 0
	v_cndmask_b32_e32 v6, v8, v6, vcc
	v_cmp_gt_u32_e32 vcc, s8, v9
	s_nop 1
	v_cndmask_b32_e32 v7, v8, v7, vcc
	v_min_u32_e32 v4, v4, v5
	v_min3_u32 v4, v4, v6, v7
	v_cmp_le_u32_e32 vcc, s100, v4
	s_nop 3
	s_cmp_eq_u64 vcc, -1
	s_cbranch_scc1 .Lfb_all_in
	s_sleep 1
	s_sub_u32 s13, s13, 1
	s_cmp_lg_u32 s13, 0
	s_cbranch_scc1 .Lfb_spin_all
